# pool horizontal-window shuffles: all 16 bpermutes of a level issued before one wait (was 8 serialized LDS round trips per level)
# speedup vs baseline: 1.0120x; 1.0026x over previous
.LBB0_798:
	v_cmp_lt_i32_e64 s[44:45], s10, v56
	v_mov_b32_e32 v26, s10
	v_subrev_u32_e32 v64, s10, v227
	v_cndmask_b32_e64 v26, 0, v26, s[44:45]
	v_cmp_lt_i32_e64 s[44:45], v64, v54
	v_add_lshl_u32 v26, v26, v227, 2
	v_cmp_lt_i32_e64 s[42:43], s10, v51
	s_nop 0
	v_cndmask_b32_e64 v64, v64, v227, s[44:45]
	v_lshlrev_b32_e32 v64, 2, v64
	v_cmp_gt_i32_e64 s[44:45], s10, v50
	s_lshl_b32 s10, s10, 1
	v_cmp_ge_i32_e32 vcc, s10, v57
	ds_bpermute_b32 v196, v26, v10
	ds_bpermute_b32 v197, v26, v11
	ds_bpermute_b32 v198, v26, v12
	ds_bpermute_b32 v199, v26, v13
	ds_bpermute_b32 v200, v26, v14
	ds_bpermute_b32 v201, v26, v15
	ds_bpermute_b32 v202, v26, v16
	ds_bpermute_b32 v203, v26, v17
	ds_bpermute_b32 v204, v64, v18
	ds_bpermute_b32 v205, v64, v19
	ds_bpermute_b32 v206, v64, v20
	ds_bpermute_b32 v207, v64, v21
	ds_bpermute_b32 v208, v64, v22
	ds_bpermute_b32 v209, v64, v23
	ds_bpermute_b32 v210, v64, v24
	s_waitcnt lgkmcnt(7)
	v_cndmask_b32_e64 v196, 0, v196, s[42:43]
	v_add_f32_e32 v10, v10, v196
	v_cndmask_b32_e64 v197, 0, v197, s[42:43]
	v_add_f32_e32 v11, v11, v197
	v_cndmask_b32_e64 v198, 0, v198, s[42:43]
	v_add_f32_e32 v12, v12, v198
	v_cndmask_b32_e64 v199, 0, v199, s[42:43]
	v_add_f32_e32 v13, v13, v199
	v_cndmask_b32_e64 v200, 0, v200, s[42:43]
	v_add_f32_e32 v14, v14, v200
	v_cndmask_b32_e64 v201, 0, v201, s[42:43]
	v_add_f32_e32 v15, v15, v201
	v_cndmask_b32_e64 v202, 0, v202, s[42:43]
	v_add_f32_e32 v16, v16, v202
	v_cndmask_b32_e64 v203, 0, v203, s[42:43]
	v_add_f32_e32 v17, v17, v203
	ds_bpermute_b32 v211, v64, v25
	s_waitcnt lgkmcnt(1)
	v_cndmask_b32_e64 v204, v204, 0, s[44:45]
	v_add_f32_e32 v18, v18, v204
	v_cndmask_b32_e64 v205, v205, 0, s[44:45]
	v_add_f32_e32 v19, v19, v205
	v_cndmask_b32_e64 v206, v206, 0, s[44:45]
	v_add_f32_e32 v20, v20, v206
	v_cndmask_b32_e64 v207, v207, 0, s[44:45]
	v_add_f32_e32 v21, v21, v207
	v_cndmask_b32_e64 v208, v208, 0, s[44:45]
	v_add_f32_e32 v22, v22, v208
	v_cndmask_b32_e64 v209, v209, 0, s[44:45]
	v_add_f32_e32 v23, v23, v209
	v_cndmask_b32_e64 v210, v210, 0, s[44:45]
	v_add_f32_e32 v24, v24, v210
	s_waitcnt lgkmcnt(0)
	v_cndmask_b32_e64 v211, v211, 0, s[44:45]
	v_add_f32_e32 v25, v25, v211
	s_or_b64 s[46:47], vcc, s[46:47]
	s_andn2_b64 exec, exec, s[46:47]
	s_cbranch_execnz .LBB0_798
	s_or_b64 exec, exec, s[46:47]
